# CL/CC epilogue: eight subln-gamma loads issued together up front
# baseline (speedup 1.0000x reference)
.LBB0_465:
	ds_bpermute_b32 v2, v161, v98
	s_waitcnt vmcnt(3)
	v_sub_f32_e32 v83, 1.0, v168
	v_ashrrev_i32_e32 v147, 31, v146
	v_lshlrev_b64 v[0:1], 18, v[146:147]
	v_lshl_add_u64 v[0:1], s[38:39], 0, v[0:1]
	s_waitcnt lgkmcnt(0)
	v_add_f32_e32 v2, v98, v2
	ds_bpermute_b32 v3, v162, v2
	s_lshl_b64 s[4:5], s[12:13], 12
	v_readlane_b32 s0, v255, 26
	v_lshl_add_u64 v[0:1], v[0:1], 0, s[4:5]
	v_readlane_b32 s1, v255, 27
	s_waitcnt lgkmcnt(0)
	v_add_f32_e32 v2, v2, v3
	v_div_scale_f32 v3, s[6:7], v2, v2, 1.0
	v_rcp_f32_e32 v4, v3
	s_add_u32 s4, s38, s0
	s_addc_u32 s5, s39, s1
	s_add_u32 s100, s4, 0x1272a980
	s_addc_u32 s101, s5, 0
	v_lshlrev_b32_e32 v112, 2, v160
	global_load_dwordx4 v[114:117], v112, s[100:101]
	global_load_dwordx4 v[118:121], v112, s[100:101] offset:64
	global_load_dwordx4 v[122:125], v112, s[100:101] offset:128
	global_load_dwordx4 v[126:129], v112, s[100:101] offset:192
	global_load_dwordx4 v[130:133], v112, s[100:101] offset:256
	global_load_dwordx4 v[134:137], v112, s[100:101] offset:320
	global_load_dwordx4 v[138:141], v112, s[100:101] offset:384
	global_load_dwordx4 v[142:145], v112, s[100:101] offset:448
	s_lshl_b32 s82, s82, 1
	v_fma_f32 v5, -v3, v4, 1.0
	v_fmac_f32_e32 v4, v5, v4
	v_div_scale_f32 v5, vcc, 1.0, v2, 1.0
	v_mul_f32_e32 v6, v5, v4
	v_fma_f32 v7, -v3, v6, v5
	v_fmac_f32_e32 v6, v7, v4
	v_fma_f32 v3, -v3, v6, v5
	v_div_fmas_f32 v3, v3, v4, v6
	v_div_fixup_f32 v2, v3, v2, 1.0
	ds_bpermute_b32 v3, v161, v17
	v_lshl_add_u64 v[0:1], v[0:1], 0, s[82:83]
	s_mov_b32 s0, 0x26b4b000
	s_waitcnt lgkmcnt(0)
	v_add_f32_e32 v3, v17, v3
	ds_bpermute_b32 v4, v162, v3
	s_waitcnt lgkmcnt(0)
	v_add_f32_e32 v3, v3, v4
	v_div_scale_f32 v4, s[6:7], v3, v3, 1.0
	v_rcp_f32_e32 v5, v4
	s_mov_b64 s[6:7], 0x26b4be00
	v_fma_f32 v6, -v4, v5, 1.0
	v_fmac_f32_e32 v5, v6, v5
	v_div_scale_f32 v6, vcc, 1.0, v3, 1.0
	v_mul_f32_e32 v7, v6, v5
	v_fma_f32 v8, -v4, v7, v6
	v_fmac_f32_e32 v7, v8, v5
	v_fma_f32 v4, -v4, v7, v6
	v_div_fmas_f32 v4, v4, v5, v7
	v_div_fixup_f32 v82, v4, v3, 1.0
	v_pk_mul_f32 v[6:7], v[78:79], v[82:83] op_sel_hi:[1,0]
	v_pk_mul_f32 v[4:5], v[80:81], v[82:83] op_sel_hi:[1,0]
	v_pk_mul_f32 v[6:7], v[150:151], v[6:7] op_sel_hi:[0,1]
	v_pk_fma_f32 v[18:19], v[70:71], v[2:3], v[6:7] op_sel_hi:[1,0,1] neg_lo:[0,0,1] neg_hi:[0,0,1]
	v_pk_mul_f32 v[6:7], v[74:75], v[82:83] op_sel_hi:[1,0]
	v_pk_mul_f32 v[4:5], v[150:151], v[4:5] op_sel_hi:[0,1]
	v_pk_mul_f32 v[6:7], v[150:151], v[6:7] op_sel_hi:[0,1]
	v_pk_fma_f32 v[8:9], v[72:73], v[2:3], v[4:5] op_sel_hi:[1,0,1] neg_lo:[0,0,1] neg_hi:[0,0,1]
	v_pk_mul_f32 v[4:5], v[76:77], v[82:83] op_sel_hi:[1,0]
	v_pk_fma_f32 v[6:7], v[66:67], v[2:3], v[6:7] op_sel_hi:[1,0,1] neg_lo:[0,0,1] neg_hi:[0,0,1]
	v_pk_mul_f32 v[4:5], v[150:151], v[4:5] op_sel_hi:[0,1]
	v_mov_b32_e32 v20, v19
	v_mov_b32_e32 v21, v7
	v_pk_fma_f32 v[4:5], v[68:69], v[2:3], v[4:5] op_sel_hi:[1,0,1] neg_lo:[0,0,1] neg_hi:[0,0,1]
	v_mov_b32_e32 v10, v18
	v_mov_b32_e32 v11, v6
	v_pk_mul_f32 v[20:21], v[20:21], v[20:21]
	v_pk_mul_f32 v[46:47], v[46:47], v[82:83] op_sel_hi:[1,0]
	v_pk_fma_f32 v[10:11], v[10:11], v[10:11], v[20:21]
	v_mov_b32_e32 v20, v8
	v_mov_b32_e32 v21, v4
	v_pk_fma_f32 v[10:11], v[20:21], v[20:21], v[10:11]
	v_mov_b32_e32 v20, v9
	v_mov_b32_e32 v21, v5
	v_pk_fma_f32 v[66:67], v[20:21], v[20:21], v[10:11]
	v_pk_mul_f32 v[10:11], v[64:65], v[82:83] op_sel_hi:[1,0]
	v_pk_mul_f32 v[20:21], v[62:63], v[82:83] op_sel_hi:[1,0]
	v_pk_mul_f32 v[10:11], v[150:151], v[10:11] op_sel_hi:[0,1]
	v_pk_mul_f32 v[62:63], v[150:151], v[20:21] op_sel_hi:[0,1]
	v_pk_fma_f32 v[20:21], v[56:57], v[2:3], v[10:11] op_sel_hi:[1,0,1] neg_lo:[0,0,1] neg_hi:[0,0,1]
	v_pk_mul_f32 v[56:57], v[58:59], v[82:83] op_sel_hi:[1,0]
	v_pk_fma_f32 v[54:55], v[54:55], v[2:3], v[62:63] op_sel_hi:[1,0,1] neg_lo:[0,0,1] neg_hi:[0,0,1]
	v_pk_mul_f32 v[56:57], v[150:151], v[56:57] op_sel_hi:[0,1]
	v_pk_mul_f32 v[10:11], v[60:61], v[82:83] op_sel_hi:[1,0]
	v_pk_fma_f32 v[50:51], v[50:51], v[2:3], v[56:57] op_sel_hi:[1,0,1] neg_lo:[0,0,1] neg_hi:[0,0,1]
	v_pk_mul_f32 v[42:43], v[42:43], v[82:83] op_sel_hi:[1,0]
	v_pk_mul_f32 v[10:11], v[150:151], v[10:11] op_sel_hi:[0,1]
	v_mov_b32_e32 v56, v51
	v_mov_b32_e32 v57, v55
	v_pk_mul_f32 v[46:47], v[150:151], v[46:47] op_sel_hi:[0,1]
	v_pk_mul_f32 v[44:45], v[44:45], v[82:83] op_sel_hi:[1,0]
	v_pk_mul_f32 v[42:43], v[150:151], v[42:43] op_sel_hi:[0,1]
	v_pk_mul_f32 v[30:31], v[30:31], v[82:83] op_sel_hi:[1,0]
	v_pk_fma_f32 v[10:11], v[52:53], v[2:3], v[10:11] op_sel_hi:[1,0,1] neg_lo:[0,0,1] neg_hi:[0,0,1]
	v_mov_b32_e32 v52, v50
	v_mov_b32_e32 v53, v54
	v_pk_mul_f32 v[56:57], v[56:57], v[56:57]
	v_pk_mul_f32 v[48:49], v[48:49], v[82:83] op_sel_hi:[1,0]
	v_pk_fma_f32 v[38:39], v[38:39], v[2:3], v[46:47] op_sel_hi:[1,0,1] neg_lo:[0,0,1] neg_hi:[0,0,1]
	v_pk_mul_f32 v[44:45], v[150:151], v[44:45] op_sel_hi:[0,1]
	v_pk_fma_f32 v[34:35], v[34:35], v[2:3], v[42:43] op_sel_hi:[1,0,1] neg_lo:[0,0,1] neg_hi:[0,0,1]
	v_pk_mul_f32 v[30:31], v[150:151], v[30:31] op_sel_hi:[0,1]
	v_pk_mul_f32 v[12:13], v[12:13], v[82:83] op_sel_hi:[1,0]
	v_pk_fma_f32 v[52:53], v[52:53], v[52:53], v[56:57]
	v_mov_b32_e32 v56, v10
	v_mov_b32_e32 v57, v20
	v_pk_mul_f32 v[48:49], v[150:151], v[48:49] op_sel_hi:[0,1]
	v_pk_fma_f32 v[36:37], v[36:37], v[2:3], v[44:45] op_sel_hi:[1,0,1] neg_lo:[0,0,1] neg_hi:[0,0,1]
	v_mov_b32_e32 v44, v35
	v_mov_b32_e32 v45, v39
	v_pk_fma_f32 v[26:27], v[26:27], v[2:3], v[30:31] op_sel_hi:[1,0,1] neg_lo:[0,0,1] neg_hi:[0,0,1]
	v_pk_mul_f32 v[14:15], v[14:15], v[82:83] op_sel_hi:[1,0]
	v_pk_mul_f32 v[30:31], v[150:151], v[12:13] op_sel_hi:[0,1]
	v_pk_fma_f32 v[52:53], v[56:57], v[56:57], v[52:53]
	v_mov_b32_e32 v56, v11
	v_mov_b32_e32 v57, v21
	v_pk_fma_f32 v[40:41], v[40:41], v[2:3], v[48:49] op_sel_hi:[1,0,1] neg_lo:[0,0,1] neg_hi:[0,0,1]
	v_mov_b32_e32 v42, v34
	v_mov_b32_e32 v43, v38
	v_pk_mul_f32 v[44:45], v[44:45], v[44:45]
	v_pk_mul_f32 v[32:33], v[32:33], v[82:83] op_sel_hi:[1,0]
	v_pk_mul_f32 v[12:13], v[150:151], v[14:15] op_sel_hi:[0,1]
	v_pk_fma_f32 v[14:15], v[22:23], v[2:3], v[30:31] op_sel_hi:[1,0,1] neg_lo:[0,0,1] neg_hi:[0,0,1]
	v_pk_fma_f32 v[52:53], v[56:57], v[56:57], v[52:53]
	v_pk_fma_f32 v[42:43], v[42:43], v[42:43], v[44:45]
	v_mov_b32_e32 v44, v36
	v_mov_b32_e32 v45, v40
	v_pk_mul_f32 v[32:33], v[150:151], v[32:33] op_sel_hi:[0,1]
	v_mov_b32_e32 v22, v15
	v_mov_b32_e32 v23, v27
	v_add_f32_e32 v17, v66, v67
	v_pk_fma_f32 v[42:43], v[44:45], v[44:45], v[42:43]
	v_mov_b32_e32 v44, v37
	v_mov_b32_e32 v45, v41
	v_pk_fma_f32 v[28:29], v[28:29], v[2:3], v[32:33] op_sel_hi:[1,0,1] neg_lo:[0,0,1] neg_hi:[0,0,1]
	v_pk_fma_f32 v[12:13], v[24:25], v[2:3], v[12:13] op_sel_hi:[1,0,1] neg_lo:[0,0,1] neg_hi:[0,0,1]
	v_mov_b32_e32 v2, v14
	v_mov_b32_e32 v3, v26
	v_pk_mul_f32 v[22:23], v[22:23], v[22:23]
	v_add_f32_e32 v17, v53, v17
	v_pk_fma_f32 v[42:43], v[44:45], v[44:45], v[42:43]
	v_pk_fma_f32 v[2:3], v[2:3], v[2:3], v[22:23]
	v_mov_b32_e32 v22, v12
	v_mov_b32_e32 v23, v28
	v_add_f32_e32 v17, v52, v17
	v_pk_fma_f32 v[2:3], v[22:23], v[22:23], v[2:3]
	v_mov_b32_e32 v22, v13
	v_mov_b32_e32 v23, v29
	v_add_f32_e32 v17, v43, v17
	v_pk_fma_f32 v[2:3], v[22:23], v[22:23], v[2:3]
	v_add_f32_e32 v17, v42, v17
	v_add_f32_e32 v3, v3, v17
	v_add_f32_e32 v17, v2, v3
	v_lshlrev_b32_e32 v2, 12, v159
	v_lshl_or_b32 v2, v157, 16, v2
	v_mov_b32_e32 v3, v16
	v_lshl_add_u64 v[0:1], v[0:1], 0, v[2:3]
	ds_bpermute_b32 v2, v161, v17
	s_waitcnt lgkmcnt(0)
	v_add_f32_e32 v2, v17, v2
	ds_bpermute_b32 v3, v162, v2
	s_waitcnt lgkmcnt(0)
	v_add_f32_e32 v2, v2, v3
	v_mov_b32_e32 v3, 0x358637bd
	v_fmamk_f32 v2, v2, 0x3c000000, v3
	v_cmp_gt_f32_e32 vcc, s54, v2
	v_mul_f32_e32 v3, 0x4b800000, v2
	s_nop 0
	v_cndmask_b32_e32 v2, v2, v3, vcc
	v_rsq_f32_e32 v2, v2
	s_nop 0
	v_mul_f32_e32 v3, 0x45800000, v2
	v_cndmask_b32_e32 v2, v2, v3, vcc
	v_mul_f32_e32 v24, v83, v2
	v_lshlrev_b32_e32 v2, 1, v160
	v_mov_b32_e32 v3, v16
	v_lshl_add_u64 v[30:31], v[0:1], 0, v[2:3]
	v_lshlrev_b32_e32 v0, 2, v160
	v_mov_b32_e32 v1, v16
	v_lshl_add_u64 v[0:1], s[4:5], 0, v[0:1]
	s_mov_b64 s[4:5], 0x1272a980
	v_lshl_add_u64 v[32:33], v[0:1], 0, s[4:5]
	s_mov_b32 s4, 0x1272a000
	v_add_co_u32_e32 v0, vcc, s4, v0
	v_pk_mul_f32 v[18:19], v[18:19], v[24:25] op_sel_hi:[1,0]
	s_nop 0
	v_addc_co_u32_e32 v1, vcc, 0, v1, vcc
	v_pk_mul_f32 v[8:9], v[8:9], v[24:25] op_sel_hi:[1,0]
	v_pk_mul_f32 v[6:7], v[6:7], v[24:25] op_sel_hi:[1,0]
	v_pk_mul_f32 v[4:5], v[4:5], v[24:25] op_sel_hi:[1,0]
	v_lshl_add_u64 v[22:23], v[30:31], 0, s[6:7]
	s_waitcnt vmcnt(0)
	v_pk_mul_f32 v[2:3], v[116:117], v[8:9]
	v_pk_mul_f32 v[0:1], v[114:115], v[18:19]
	s_nop 0
	v_cvt_pk_bf16_f32 v0, v0, v1
	v_cvt_pk_bf16_f32 v1, v2, v3
	v_add_co_u32_e32 v2, vcc, s0, v30
	s_nop 1
	v_addc_co_u32_e32 v3, vcc, 0, v31, vcc
	global_store_dwordx2 v[2:3], v[0:1], off offset:3584
	v_pk_mul_f32 v[2:3], v[120:121], v[4:5]
	v_pk_mul_f32 v[0:1], v[118:119], v[6:7]
	v_pk_mul_f32 v[4:5], v[54:55], v[24:25] op_sel_hi:[1,0]
	v_cvt_pk_bf16_f32 v0, v0, v1
	v_cvt_pk_bf16_f32 v1, v2, v3
	global_store_dwordx2 v[22:23], v[0:1], off offset:32
	v_pk_mul_f32 v[6:7], v[20:21], v[24:25] op_sel_hi:[1,0]
	v_pk_mul_f32 v[0:1], v[122:123], v[4:5]
	v_pk_mul_f32 v[2:3], v[124:125], v[6:7]
	v_cvt_pk_bf16_f32 v0, v0, v1
	v_cvt_pk_bf16_f32 v1, v2, v3
	global_store_dwordx2 v[22:23], v[0:1], off offset:64
	v_pk_mul_f32 v[4:5], v[50:51], v[24:25] op_sel_hi:[1,0]
	v_pk_mul_f32 v[6:7], v[10:11], v[24:25] op_sel_hi:[1,0]
	v_pk_mul_f32 v[0:1], v[126:127], v[4:5]
	v_pk_mul_f32 v[2:3], v[128:129], v[6:7]
	v_cvt_pk_bf16_f32 v0, v0, v1
	v_cvt_pk_bf16_f32 v1, v2, v3
	global_store_dwordx2 v[22:23], v[0:1], off offset:96
	v_pk_mul_f32 v[4:5], v[38:39], v[24:25] op_sel_hi:[1,0]
	v_pk_mul_f32 v[6:7], v[40:41], v[24:25] op_sel_hi:[1,0]
	v_pk_mul_f32 v[0:1], v[130:131], v[4:5]
	v_pk_mul_f32 v[2:3], v[132:133], v[6:7]
	v_cvt_pk_bf16_f32 v0, v0, v1
	v_cvt_pk_bf16_f32 v1, v2, v3
	global_store_dwordx2 v[22:23], v[0:1], off offset:128
	v_pk_mul_f32 v[4:5], v[34:35], v[24:25] op_sel_hi:[1,0]
	v_pk_mul_f32 v[6:7], v[36:37], v[24:25] op_sel_hi:[1,0]
	v_pk_mul_f32 v[0:1], v[134:135], v[4:5]
	v_pk_mul_f32 v[2:3], v[136:137], v[6:7]
	v_cvt_pk_bf16_f32 v0, v0, v1
	v_cvt_pk_bf16_f32 v1, v2, v3
	global_store_dwordx2 v[22:23], v[0:1], off offset:160
	v_pk_mul_f32 v[4:5], v[26:27], v[24:25] op_sel_hi:[1,0]
	v_pk_mul_f32 v[6:7], v[28:29], v[24:25] op_sel_hi:[1,0]
	v_pk_mul_f32 v[0:1], v[138:139], v[4:5]
	v_pk_mul_f32 v[2:3], v[140:141], v[6:7]
	v_cvt_pk_bf16_f32 v0, v0, v1
	v_cvt_pk_bf16_f32 v1, v2, v3
	global_store_dwordx2 v[22:23], v[0:1], off offset:192
	v_pk_mul_f32 v[4:5], v[14:15], v[24:25] op_sel_hi:[1,0]
	v_pk_mul_f32 v[6:7], v[12:13], v[24:25] op_sel_hi:[1,0]
	v_pk_mul_f32 v[0:1], v[142:143], v[4:5]
	v_pk_mul_f32 v[2:3], v[144:145], v[6:7]
	v_cvt_pk_bf16_f32 v0, v0, v1
	v_cvt_pk_bf16_f32 v1, v2, v3
	global_store_dwordx2 v[22:23], v[0:1], off offset:224
	s_barrier
